# lru_scan fast path: non-temporal hint on the once-streamed ax tile loads so the L2 keeps the g / y lines shared by the paired workgroups
# baseline (speedup 1.0000x reference)
; DI void phase_lru_scan(const Params& p, LAS unsigned char* lds) {
;     ...
;     for (int u = blockIdx.x; u < 256; u += gridDim.x) {
;         const int b = u >> 6, ch = (u & 63) * 32 + chl;
;         const size_t rowbase = (size_t)b * SEQ;
;         unsigned pre[32];
; #pragma unroll
;         for (int i = 0; i < 32; ++i) pre[i] = ax[(rowbase + seg + 16 * i) * DM + ch];
;         __syncthreads();
;         if (tid < 32) sC[tid] = 0.f;
;         for (int sc = 0; sc < 8; ++sc) {
; #pragma unroll
;             for (int i = 0; i < 32; ++i) tile[(seg + 16 * i) * 32 + chl] = pre[i];
;             __syncthreads();
;             if (sc + 1 < 8) {
; #pragma unroll
;                 for (int i = 0; i < 32; ++i) pre[i] = ax[(rowbase + (sc + 1) * 512 + seg + 16 * i) * DM + ch];
;             }
;             const size_t r0 = rowbase + sc * 512 + seg * 32;
;             bf16_t gq[32];
; #pragma unroll
;             for (int t = 0; t < 32; ++t) gq[t] = big[(r0 + t) * 4096 + 2048 + ch];
.LBB0_1009:
	s_or_b64 exec, exec, s[8:9]
	v_mov_b32_e32 v4, v181
	s_and_b64 vcc, exec, s[6:7]
	s_waitcnt lgkmcnt(0)
	s_barrier
	s_cbranch_vccnz .LBB0_1026
	s_cmp_eq_u32 s18, 0x100
	s_cbranch_scc0 .Llr_orig
	s_load_dwordx2 s[6:7], s[0:1], 0xf0
	v_and_b32_e32 v126, 31, v181
	v_lshrrev_b32_e32 v113, 5, v181
	v_lshlrev_b32_e32 v112, 2, v126
	v_lshl_add_u32 v114, v113, 12, v112
	v_lshlrev_b32_e32 v127, 1, v126
	v_lshl_add_u32 v115, v113, 11, v127
	v_add_u32_e32 v115, 65536, v115
	v_lshlrev_b32_e32 v116, 2, v181
	v_add_u32_e32 v116, 98304, v116
	v_add_u32_e32 v117, 98304, v112
	v_lshrrev_b32_e32 v128, 3, v181
	v_and_b32_e32 v129, 7, v181
	v_lshlrev_b32_e32 v118, 7, v128
	v_lshl_add_u32 v118, v129, 4, v118
	v_lshlrev_b32_e32 v120, 13, v128
	v_lshl_add_u32 v120, v129, 4, v120
	v_lshrrev_b32_e32 v128, 2, v181
	v_and_b32_e32 v129, 3, v181
	v_lshlrev_b32_e32 v119, 6, v128
	v_lshl_add_u32 v119, v129, 4, v119
	v_add_u32_e32 v119, 65536, v119
	v_lshlrev_b32_e32 v121, 13, v128
	v_lshl_add_u32 v121, v129, 4, v121
	v_lshlrev_b32_e32 v122, 12, v128
	v_lshl_add_u32 v122, v129, 4, v122
	s_lshr_b32 s10, s2, 3
	s_and_b32 s9, s2, 7
	s_lshr_b32 s8, s10, 3
	s_bfe_u32 s11, s10, 0x20001
	s_lshl_b32 s11, s11, 3
	s_add_u32 s9, s9, s11
	s_lshl_b32 s9, s9, 1
	s_and_b32 s10, s10, 1
	s_or_b32 s9, s9, s10
	s_lshl_b32 s10, s8, 25
	s_lshl_b32 s11, s9, 7
	s_waitcnt lgkmcnt(0)
	s_add_u32 s12, s6, 0x13f00000
	s_addc_u32 s13, s7, 0
	s_add_u32 s12, s12, s10
	s_addc_u32 s13, s13, 0
	s_add_u32 s12, s12, s11
	s_addc_u32 s13, s13, 0
	s_lshl_b32 s11, s9, 6
	s_add_u32 s14, s6, 0xbf01000
	s_addc_u32 s15, s7, 0
	s_add_u32 s14, s14, s10
	s_addc_u32 s15, s15, 0
	s_add_u32 s14, s14, s11
	s_addc_u32 s15, s15, 0
	s_lshl_b32 s10, s8, 24
	s_add_u32 s16, s6, 0x7f00000
	s_addc_u32 s17, s7, 0
	s_add_u32 s16, s16, s10
	s_addc_u32 s17, s17, 0
	s_add_u32 s16, s16, s11
	s_addc_u32 s17, s17, 0
	s_mov_b64 s[24:25], s[12:13]
	global_load_dwordx4 v[64:67], v120, s[24:25] nt
	s_add_u32 s24, s24, 0x80000
	s_addc_u32 s25, s25, 0
	global_load_dwordx4 v[68:71], v120, s[24:25] nt
	s_add_u32 s24, s24, 0x80000
	s_addc_u32 s25, s25, 0
	global_load_dwordx4 v[72:75], v120, s[24:25] nt
	s_add_u32 s24, s24, 0x80000
	s_addc_u32 s25, s25, 0
	global_load_dwordx4 v[76:79], v120, s[24:25] nt
	s_add_u32 s24, s24, 0x80000
	s_addc_u32 s25, s25, 0
	global_load_dwordx4 v[80:83], v120, s[24:25] nt
	s_add_u32 s24, s24, 0x80000
	s_addc_u32 s25, s25, 0
	global_load_dwordx4 v[84:87], v120, s[24:25] nt
	s_add_u32 s24, s24, 0x80000
	s_addc_u32 s25, s25, 0
	global_load_dwordx4 v[88:91], v120, s[24:25] nt
	s_add_u32 s24, s24, 0x80000
	s_addc_u32 s25, s25, 0
	global_load_dwordx4 v[92:95], v120, s[24:25] nt
	s_mov_b64 s[24:25], s[14:15]
	global_load_dwordx4 v[96:99], v121, s[24:25]
	s_add_u32 s24, s24, 0x100000
	s_addc_u32 s25, s25, 0
	global_load_dwordx4 v[100:103], v121, s[24:25]
	s_add_u32 s24, s24, 0x100000
	s_addc_u32 s25, s25, 0
	global_load_dwordx4 v[104:107], v121, s[24:25]
	s_add_u32 s24, s24, 0x100000
	s_addc_u32 s25, s25, 0
	global_load_dwordx4 v[108:111], v121, s[24:25]
	s_add_u32 s12, s12, 0x400000
	s_addc_u32 s13, s13, 0
	s_add_u32 s14, s14, 0x400000
	s_addc_u32 s15, s15, 0
	v_cmp_gt_u32_e32 vcc, 32, v181
	s_and_saveexec_b64 s[26:27], vcc
	v_mov_b32_e32 v126, 0
	v_add_u32_e32 v127, 102400, v112
	ds_write_b32 v127, v126
	s_mov_b64 exec, s[26:27]
	s_mov_b64 exec, -1
	s_mov_b32 s28, 0
	s_waitcnt vmcnt(0)
.Llr_sc:
	s_barrier
	s_waitcnt vmcnt(4)
	ds_write_b128 v118, v[64:67] offset:0
	ds_write_b128 v118, v[68:71] offset:8192
	ds_write_b128 v118, v[72:75] offset:16384
	ds_write_b128 v118, v[76:79] offset:24576
	ds_write_b128 v118, v[80:83] offset:32768
	ds_write_b128 v118, v[84:87] offset:40960
	ds_write_b128 v118, v[88:91] offset:49152
	ds_write_b128 v118, v[92:95] offset:57344
	ds_write_b128 v119, v[96:99] offset:0
	ds_write_b128 v119, v[100:103] offset:8192
	ds_write_b128 v119, v[104:107] offset:16384
	ds_write_b128 v119, v[108:111] offset:24576
	s_waitcnt lgkmcnt(0)
	s_barrier
	s_cmp_eq_u32 s28, 7
	s_cbranch_scc1 .Llr_noload
	s_mov_b64 s[24:25], s[12:13]
	global_load_dwordx4 v[64:67], v120, s[24:25] nt
	s_add_u32 s24, s24, 0x80000
	s_addc_u32 s25, s25, 0
	global_load_dwordx4 v[68:71], v120, s[24:25] nt
	s_add_u32 s24, s24, 0x80000
	s_addc_u32 s25, s25, 0
	global_load_dwordx4 v[72:75], v120, s[24:25] nt
	s_add_u32 s24, s24, 0x80000
	s_addc_u32 s25, s25, 0
	global_load_dwordx4 v[76:79], v120, s[24:25] nt
	s_add_u32 s24, s24, 0x80000
	s_addc_u32 s25, s25, 0
	global_load_dwordx4 v[80:83], v120, s[24:25] nt
	s_add_u32 s24, s24, 0x80000
	s_addc_u32 s25, s25, 0
	global_load_dwordx4 v[84:87], v120, s[24:25] nt
	s_add_u32 s24, s24, 0x80000
	s_addc_u32 s25, s25, 0
	global_load_dwordx4 v[88:91], v120, s[24:25] nt
	s_add_u32 s24, s24, 0x80000
	s_addc_u32 s25, s25, 0
	global_load_dwordx4 v[92:95], v120, s[24:25] nt
	s_mov_b64 s[24:25], s[14:15]
	global_load_dwordx4 v[96:99], v121, s[24:25]
	s_add_u32 s24, s24, 0x100000
	s_addc_u32 s25, s25, 0
	global_load_dwordx4 v[100:103], v121, s[24:25]
	s_add_u32 s24, s24, 0x100000
	s_addc_u32 s25, s25, 0
	global_load_dwordx4 v[104:107], v121, s[24:25]
	s_add_u32 s24, s24, 0x100000
	s_addc_u32 s25, s25, 0
	global_load_dwordx4 v[108:111], v121, s[24:25]
	s_add_u32 s12, s12, 0x400000
	s_addc_u32 s13, s13, 0
	s_add_u32 s14, s14, 0x400000
	s_addc_u32 s15, s15, 0
